# P5 cross-XCD outputs (att, bvec) stored write-through and no L2 writeback at the seam-5 arrive
# speedup vs baseline: 1.0023x; 1.0023x over previous
.LBB0_842:
	v_fma_f32 v3, v36, s51, -v1
	v_exp_f32_e32 v3, v3
	v_fma_f32 v36, v37, s51, -v1
	v_exp_f32_e32 v36, v36
	v_fma_f32 v37, v38, s51, -v1
	v_exp_f32_e32 v37, v37
	v_fma_f32 v39, v39, s51, -v1
	v_exp_f32_e32 v39, v39
	v_fma_f32 v40, v40, s51, -v1
	v_add_f32_e32 v38, 0, v3
	v_exp_f32_e32 v40, v40
	v_fma_f32 v41, v41, s51, -v1
	v_add_f32_e32 v38, v36, v38
	v_exp_f32_e32 v41, v41
	v_fma_f32 v42, v42, s51, -v1
	v_add_f32_e32 v38, v37, v38
	v_exp_f32_e32 v42, v42
	v_fma_f32 v43, v43, s51, -v1
	v_add_f32_e32 v38, v39, v38
	v_exp_f32_e32 v43, v43
	v_fma_f32 v44, v44, s51, -v1
	v_add_f32_e32 v38, v40, v38
	v_exp_f32_e32 v44, v44
	v_fma_f32 v45, v45, s51, -v1
	v_add_f32_e32 v38, v41, v38
	v_exp_f32_e32 v45, v45
	v_add_f32_e32 v38, v42, v38
	v_add_f32_e32 v38, v43, v38
	v_add_f32_e32 v38, v44, v38
	v_add_f32_e32 v52, v45, v38
	v_fma_f32 v38, v46, s51, -v1
	v_exp_f32_e32 v46, v38
	v_fma_f32 v38, v47, s51, -v1
	v_exp_f32_e32 v47, v38
	v_fma_f32 v38, v48, s51, -v1
	v_exp_f32_e32 v48, v38
	v_cvt_pk_bf16_f32 v36, v3, v36
	v_fma_f32 v3, v49, s51, -v1
	v_cvt_pk_bf16_f32 v38, v40, v41
	v_exp_f32_e32 v3, v3
	v_fma_f32 v41, v50, s51, -v1
	v_add_f32_e32 v40, v46, v52
	v_exp_f32_e32 v41, v41
	v_fma_f32 v1, v51, s51, -v1
	v_add_f32_e32 v40, v47, v40
	v_exp_f32_e32 v1, v1
	v_add_f32_e32 v40, v48, v40
	v_cvt_pk_bf16_f32 v37, v37, v39
	v_cvt_pk_bf16_f32 v39, v42, v43
	v_add_f32_e32 v40, v3, v40
	s_lshl_b32 s10, s59, 6
	v_mfma_f32_32x32x16_bf16 v[20:35], v[92:95], v[36:39], v[20:35]
	s_add_u32 s11, s40, s18
	s_addc_u32 s15, s41, s19
	v_mov_b32_e32 v201, v2
	v_mov_b32_e32 v213, v2
	s_waitcnt vmcnt(1)
	v_mfma_f32_32x32x16_bf16 v[4:19], v[88:91], v[36:39], v[4:19]
	v_cvt_pk_bf16_f32 v38, v48, v3
	v_add_f32_e32 v3, v41, v40
	v_cvt_pk_bf16_f32 v39, v41, v1
	v_add_f32_e32 v1, v1, v3
	v_add_f32_e32 v0, v1, v0
	ds_bpermute_b32 v1, v224, v0
	v_cvt_pk_bf16_f32 v36, v44, v45
	v_cvt_pk_bf16_f32 v37, v46, v47
	s_waitcnt lgkmcnt(0)
	v_add_f32_e32 v0, v0, v1
	v_div_scale_f32 v1, s[0:1], v0, v0, 1.0
	v_rcp_f32_e32 v3, v1
	v_mfma_f32_32x32x16_bf16 v[20:35], v[84:87], v[36:39], v[20:35]
	s_lshl_b32 s0, s10, 1
	s_add_u32 s0, s11, s0
	s_addc_u32 s1, s15, 0
	s_add_i32 s14, s14, s34
	s_cmpk_lt_i32 s14, 0x100
	s_waitcnt vmcnt(0)
	v_mfma_f32_32x32x16_bf16 v[4:19], v[72:75], v[36:39], v[4:19]
	v_fma_f32 v36, -v1, v3, 1.0
	v_fmac_f32_e32 v3, v36, v3
	v_div_scale_f32 v36, vcc, 1.0, v0, 1.0
	v_mul_f32_e32 v37, v36, v3
	v_fma_f32 v38, -v1, v37, v36
	v_fmac_f32_e32 v37, v38, v3
	v_fma_f32 v1, -v1, v37, v36
	v_div_fmas_f32 v1, v1, v3, v37
	v_div_fixup_f32 v0, v1, v0, 1.0
	v_lshl_add_u64 v[36:37], s[0:1], 0, v[200:201]
	s_nop 1
	v_pk_mul_f32 v[4:5], v[4:5], v[0:1] op_sel_hi:[1,0]
	v_pk_mul_f32 v[6:7], v[6:7], v[0:1] op_sel_hi:[1,0]
	v_lshl_add_u64 v[36:37], v[36:37], 0, v[212:213]
	v_cvt_pk_bf16_f32 v4, v4, v5
	v_cvt_pk_bf16_f32 v5, v6, v7
	global_store_dwordx2 v[36:37], v[4:5], off offset:64 sc0 sc1
	v_pk_mul_f32 v[4:5], v[24:25], v[0:1] op_sel_hi:[1,0]
	v_pk_mul_f32 v[6:7], v[26:27], v[0:1] op_sel_hi:[1,0]
	v_cvt_pk_bf16_f32 v4, v4, v5
	v_cvt_pk_bf16_f32 v5, v6, v7
	global_store_dwordx2 v[36:37], v[4:5], off offset:16 sc0 sc1
	v_pk_mul_f32 v[4:5], v[8:9], v[0:1] op_sel_hi:[1,0]
	v_pk_mul_f32 v[6:7], v[10:11], v[0:1] op_sel_hi:[1,0]
	v_cvt_pk_bf16_f32 v4, v4, v5
	v_cvt_pk_bf16_f32 v5, v6, v7
	global_store_dwordx2 v[36:37], v[4:5], off offset:80 sc0 sc1
	v_pk_mul_f32 v[4:5], v[28:29], v[0:1] op_sel_hi:[1,0]
	v_pk_mul_f32 v[6:7], v[30:31], v[0:1] op_sel_hi:[1,0]
	v_cvt_pk_bf16_f32 v4, v4, v5
	v_cvt_pk_bf16_f32 v5, v6, v7
	global_store_dwordx2 v[36:37], v[4:5], off offset:32 sc0 sc1
	v_pk_mul_f32 v[4:5], v[12:13], v[0:1] op_sel_hi:[1,0]
	v_pk_mul_f32 v[6:7], v[14:15], v[0:1] op_sel_hi:[1,0]
	v_cvt_pk_bf16_f32 v4, v4, v5
	v_cvt_pk_bf16_f32 v5, v6, v7
	global_store_dwordx2 v[36:37], v[4:5], off offset:96 sc0 sc1
	v_pk_mul_f32 v[4:5], v[32:33], v[0:1] op_sel_hi:[1,0]
	v_pk_mul_f32 v[6:7], v[34:35], v[0:1] op_sel_hi:[1,0]
	v_cvt_pk_bf16_f32 v4, v4, v5
	v_cvt_pk_bf16_f32 v5, v6, v7
	v_pk_mul_f32 v[20:21], v[20:21], v[0:1] op_sel_hi:[1,0]
	v_pk_mul_f32 v[22:23], v[22:23], v[0:1] op_sel_hi:[1,0]
	global_store_dwordx2 v[36:37], v[4:5], off offset:48 sc0 sc1
	v_pk_mul_f32 v[4:5], v[16:17], v[0:1] op_sel_hi:[1,0]
	v_pk_mul_f32 v[0:1], v[18:19], v[0:1] op_sel_hi:[1,0]
	v_cvt_pk_bf16_f32 v20, v20, v21
	v_cvt_pk_bf16_f32 v21, v22, v23
	v_cvt_pk_bf16_f32 v4, v4, v5
	v_cvt_pk_bf16_f32 v5, v0, v1
	global_store_dwordx2 v[36:37], v[20:21], off sc0 sc1
	global_store_dwordx2 v[36:37], v[4:5], off offset:112 sc0 sc1
	s_cbranch_scc0 .LBB0_1071

.LBB0_1057:
	ds_bpermute_b32 v0, v224, v201
	s_lshl_b64 s[10:11], s[18:19], 1
	s_add_u32 s15, s40, s10
	s_addc_u32 s18, s41, s11
	s_lshl_b32 s1, s1, 1
	s_waitcnt lgkmcnt(0)
	v_add_f32_e32 v0, v201, v0
	v_div_scale_f32 v1, s[10:11], v0, v0, 1.0
	v_rcp_f32_e32 v3, v1
	s_add_u32 s10, s15, s1
	s_addc_u32 s11, s18, 0
	v_mov_b32_e32 v201, v2
	v_fma_f32 v4, -v1, v3, 1.0
	v_fmac_f32_e32 v3, v4, v3
	v_div_scale_f32 v4, vcc, 1.0, v0, 1.0
	v_mul_f32_e32 v5, v4, v3
	v_fma_f32 v6, -v1, v5, v4
	v_fmac_f32_e32 v5, v6, v3
	v_fma_f32 v1, -v1, v5, v4
	v_div_fmas_f32 v1, v1, v3, v5
	v_div_fixup_f32 v0, v1, v0, 1.0
	v_lshl_add_u64 v[4:5], s[10:11], 0, v[200:201]
	v_mov_b32_e32 v213, v2
	v_pk_mul_f32 v[6:7], v[16:17], v[0:1] op_sel_hi:[1,0]
	v_pk_mul_f32 v[8:9], v[18:19], v[0:1] op_sel_hi:[1,0]
	v_lshl_add_u64 v[4:5], v[4:5], 0, v[212:213]
	v_cvt_pk_bf16_f32 v6, v6, v7
	v_cvt_pk_bf16_f32 v7, v8, v9
	global_store_dwordx2 v[4:5], v[6:7], off sc0 sc1
	v_pk_mul_f32 v[6:7], v[32:33], v[0:1] op_sel_hi:[1,0]
	v_pk_mul_f32 v[8:9], v[34:35], v[0:1] op_sel_hi:[1,0]
	v_cvt_pk_bf16_f32 v6, v6, v7
	v_cvt_pk_bf16_f32 v7, v8, v9
	global_store_dwordx2 v[4:5], v[6:7], off offset:64 sc0 sc1
	v_pk_mul_f32 v[6:7], v[20:21], v[0:1] op_sel_hi:[1,0]
	v_pk_mul_f32 v[8:9], v[22:23], v[0:1] op_sel_hi:[1,0]
	v_cvt_pk_bf16_f32 v6, v6, v7
	v_cvt_pk_bf16_f32 v7, v8, v9
	s_ashr_i32 s1, s0, 31
	global_store_dwordx2 v[4:5], v[6:7], off offset:16 sc0 sc1
	v_pk_mul_f32 v[6:7], v[36:37], v[0:1] op_sel_hi:[1,0]
	v_pk_mul_f32 v[8:9], v[38:39], v[0:1] op_sel_hi:[1,0]
	s_lshl_b64 s[0:1], s[0:1], 17
	v_cvt_pk_bf16_f32 v6, v6, v7
	v_cvt_pk_bf16_f32 v7, v8, v9
	s_add_u32 s0, s0, s8
	global_store_dwordx2 v[4:5], v[6:7], off offset:80 sc0 sc1
	v_pk_mul_f32 v[6:7], v[24:25], v[0:1] op_sel_hi:[1,0]
	v_pk_mul_f32 v[8:9], v[26:27], v[0:1] op_sel_hi:[1,0]
	s_addc_u32 s1, s1, s9
	v_cvt_pk_bf16_f32 v6, v6, v7
	v_cvt_pk_bf16_f32 v7, v8, v9
	s_lshl_b64 s[18:19], s[0:1], 1
	global_store_dwordx2 v[4:5], v[6:7], off offset:32 sc0 sc1
	v_pk_mul_f32 v[6:7], v[40:41], v[0:1] op_sel_hi:[1,0]
	v_pk_mul_f32 v[8:9], v[42:43], v[0:1] op_sel_hi:[1,0]
	s_add_u32 s0, s2, s18
	v_cvt_pk_bf16_f32 v6, v6, v7
	v_cvt_pk_bf16_f32 v7, v8, v9
	s_addc_u32 s1, s3, s19
	s_lshl_b32 s10, s59, 7
	global_store_dwordx2 v[4:5], v[6:7], off offset:96 sc0 sc1
	v_pk_mul_f32 v[6:7], v[28:29], v[0:1] op_sel_hi:[1,0]
	v_pk_mul_f32 v[8:9], v[30:31], v[0:1] op_sel_hi:[1,0]
	s_add_u32 s0, s0, s10
	v_cvt_pk_bf16_f32 v6, v6, v7
	v_cvt_pk_bf16_f32 v7, v8, v9
	s_addc_u32 s1, s1, 0
	s_ashr_i32 s15, s14, 31
	global_store_dwordx2 v[4:5], v[6:7], off offset:48 sc0 sc1
	v_pk_mul_f32 v[6:7], v[44:45], v[0:1] op_sel_hi:[1,0]
	v_pk_mul_f32 v[0:1], v[46:47], v[0:1] op_sel_hi:[1,0]
	s_lshl_b64 s[10:11], s[14:15], 15
	v_cvt_pk_bf16_f32 v6, v6, v7
	v_cvt_pk_bf16_f32 v7, v0, v1
	s_add_u32 s20, s26, s10
	global_store_dwordx2 v[4:5], v[6:7], off offset:112 sc0 sc1
	s_addc_u32 s21, s27, s11
	global_load_dwordx4 v[4:7], v208, s[20:21]
	v_lshl_add_u64 v[0:1], s[0:1], 0, v[200:201]
	v_mov_b32_e32 v205, v2
	v_lshl_add_u64 v[0:1], v[0:1], 0, v[204:205]
	global_load_dwordx4 v[56:59], v[0:1], off
	global_load_dwordx4 v[8:11], v208, s[20:21] offset:1024
	global_load_dwordx4 v[52:55], v[0:1], off offset:32
	global_load_dwordx4 v[12:15], v208, s[20:21] offset:2048
	s_add_u32 s0, s43, s10
	s_addc_u32 s1, s45, s11
	v_mov_b32_e32 v209, v2
	s_waitcnt vmcnt(16)
	v_lshl_add_u64 v[168:169], s[0:1], 0, v[208:209]
	v_lshl_add_u64 v[82:83], v[168:169], 0, s[12:13]
	s_waitcnt vmcnt(3)
	v_mfma_f32_32x32x16_bf16 v[22:37], v[4:7], v[56:59], 0
	global_load_dwordx4 v[64:67], v[0:1], off offset:64
	global_load_dwordx4 v[4:7], v208, s[20:21] offset:3072
	global_load_dwordx4 v[60:63], v[0:1], off offset:96
	global_load_dwordx4 v[38:41], v208, s[0:1]
	global_load_dwordx4 v[42:45], v208, s[0:1] offset:1024
	global_load_dwordx4 v[46:49], v208, s[0:1] offset:2048
	v_lshl_add_u64 v[0:1], s[20:21], 0, v[208:209]
	v_add_co_u32_e32 v80, vcc, s48, v0
	v_lshl_add_u64 v[50:51], v[0:1], 0, s[12:13]
	s_nop 0
	v_addc_co_u32_e32 v81, vcc, 0, v1, vcc
	global_load_dwordx4 v[120:123], v208, s[0:1] offset:3072
	global_load_dwordx4 v[72:75], v[80:81], off offset:-4096
	global_load_dwordx4 v[76:79], v[50:51], off offset:1024
	global_load_dwordx4 v[96:99], v[50:51], off offset:2048
	s_waitcnt vmcnt(11)
	v_mfma_f32_32x32x16_bf16 v[22:37], v[8:11], v[52:55], v[22:37]
	v_add_co_u32_e64 v100, s[0:1], s48, v168
	s_nop 1
	v_addc_co_u32_e64 v101, s[0:1], 0, v169, s[0:1]
	s_waitcnt vmcnt(9)
	v_mfma_f32_32x32x16_bf16 v[22:37], v[12:15], v[64:67], v[22:37]
	s_waitcnt vmcnt(7)
	v_mfma_f32_32x32x16_bf16 v[22:37], v[4:7], v[60:63], v[22:37]
	s_nop 11
	v_max_f32_e32 v3, v23, v23
	v_max_f32_e32 v4, v22, v22
	v_max_f32_e32 v3, v4, v3
	v_max3_f32 v3, v3, v24, v25
	v_max3_f32 v3, v3, v26, v27
	v_max3_f32 v3, v3, v28, v29
	v_max3_f32 v3, v3, v30, v31
	v_max3_f32 v3, v3, v32, v33
	v_max3_f32 v3, v3, v34, v35
	v_max3_f32 v3, v3, v36, v37
	v_mul_f32_e32 v3, 0x3e38aa3b, v3
	ds_bpermute_b32 v4, v224, v3
	s_waitcnt lgkmcnt(0)
	v_max3_f32 v3, v3, v4, s53
	v_fma_f32 v5, v22, s51, -v3
	v_fma_f32 v6, v23, s51, -v3
	v_exp_f32_e32 v21, v5
	v_fma_f32 v7, v24, s51, -v3
	v_exp_f32_e32 v22, v6
	v_fma_f32 v8, v25, s51, -v3
	v_exp_f32_e32 v23, v7
	v_fma_f32 v9, v26, s51, -v3
	v_exp_f32_e32 v24, v8
	v_fma_f32 v20, v27, s51, -v3
	v_exp_f32_e32 v25, v9
	v_add_f32_e32 v5, 0, v21
	v_add_f32_e32 v26, v22, v5
	v_exp_f32_e32 v20, v20
	v_fma_f32 v27, v28, s51, -v3
	v_add_f32_e32 v26, v23, v26
	v_exp_f32_e32 v27, v27
	v_fma_f32 v28, v29, s51, -v3
	v_add_f32_e32 v26, v24, v26
	v_exp_f32_e32 v28, v28
	v_fma_f32 v29, v30, s51, -v3
	v_add_f32_e32 v26, v25, v26
	v_exp_f32_e32 v88, v29
	v_fma_f32 v29, v31, s51, -v3
	v_add_f32_e32 v26, v20, v26
	v_exp_f32_e32 v89, v29
	v_fma_f32 v29, v32, s51, -v3
	v_add_f32_e32 v26, v27, v26
	v_exp_f32_e32 v90, v29
	v_fma_f32 v29, v33, s51, -v3
	v_add_f32_e32 v26, v28, v26
	v_exp_f32_e32 v91, v29
	v_sub_f32_e32 v4, 0xf149f2ca, v3
	v_add_f32_e32 v26, v88, v26
	v_exp_f32_e32 v4, v4
	v_add_f32_e32 v26, v89, v26
	v_add_f32_e32 v26, v90, v26
	v_cmp_lt_f32_e32 vcc, s53, v3
	v_add_f32_e32 v84, v91, v26
	v_fma_f32 v26, v34, s51, -v3
	s_cmp_eq_u64 vcc, 0
	v_exp_f32_e32 v92, v26
	v_mul_f32_e32 v4, 0, v4
	s_cselect_b64 vcc, -1, 0
	v_cndmask_b32_e64 v4, v4, 0, vcc
	v_fma_f32 v26, v35, s51, -v3
	v_mov_b32_e32 v5, v4
	v_mov_b32_e32 v6, v4
	v_mov_b32_e32 v7, v4
	v_mov_b32_e32 v8, v4
	v_mov_b32_e32 v9, v4
	v_mov_b32_e32 v10, v4
	v_mov_b32_e32 v11, v4
	v_mov_b32_e32 v12, v4
	v_mov_b32_e32 v13, v4
	v_mov_b32_e32 v14, v4
	v_mov_b32_e32 v15, v4
	v_mov_b32_e32 v16, v4
	v_mov_b32_e32 v17, v4
	v_mov_b32_e32 v18, v4
	v_mov_b32_e32 v19, v4
	v_exp_f32_e32 v93, v26
	v_fma_f32 v26, v36, s51, -v3
	v_cvt_pk_bf16_f32 v68, v21, v22
	v_cvt_pk_bf16_f32 v69, v23, v24
	v_cvt_pk_bf16_f32 v70, v25, v20
	v_cvt_pk_bf16_f32 v71, v27, v28
	v_exp_f32_e32 v36, v26
	v_fma_f32 v37, v37, s51, -v3
	s_waitcnt vmcnt(6)
	v_mfma_f32_32x32x16_bf16 v[20:35], v[38:41], v[68:71], v[4:19]
	v_add_f32_e32 v38, v92, v84
	global_load_dwordx4 v[84:87], v[82:83], off offset:1024
	global_load_dwordx4 v[124:127], v[50:51], off offset:3072
	v_exp_f32_e32 v37, v37
	v_add_f32_e32 v38, v93, v38
	v_add_f32_e32 v38, v36, v38
	v_cvt_pk_bf16_f32 v132, v88, v89
	v_add_f32_e32 v38, v37, v38
	v_cvt_pk_bf16_f32 v133, v90, v91
	v_cvt_pk_bf16_f32 v134, v92, v93
	v_cvt_pk_bf16_f32 v135, v36, v37
	v_add_f32_e32 v164, v4, v38
	s_waitcnt vmcnt(6)
	v_mfma_f32_32x32x16_bf16 v[4:19], v[46:49], v[68:71], v[4:19]
	global_load_dwordx4 v[88:91], v[82:83], off offset:2048
	global_load_dwordx4 v[144:147], v[82:83], off offset:3072
	global_load_dwordx4 v[68:71], v[80:81], off
	global_load_dwordx4 v[116:119], v[100:101], off
	global_load_dwordx4 v[108:111], v[100:101], off offset:1024
	global_load_dwordx4 v[156:159], v[80:81], off offset:1024
	global_load_dwordx4 v[148:151], v[80:81], off offset:2048
	global_load_dwordx4 v[92:95], v[100:101], off offset:-4096
	global_load_dwordx4 v[160:163], v[80:81], off offset:3072
	global_load_dwordx4 v[140:143], v[100:101], off offset:2048
	global_load_dwordx4 v[128:131], v[100:101], off offset:3072
	v_cndmask_b32_e32 v3, v3, v225, vcc
	v_mfma_f32_32x32x16_bf16 v[20:35], v[42:45], v[132:135], v[20:35]
	s_waitcnt vmcnt(15)
	v_mfma_f32_32x32x16_bf16 v[36:51], v[72:75], v[56:59], 0
	v_add_co_u32_e64 v72, s[0:1], s54, v0
	s_nop 1
	v_addc_co_u32_e64 v73, s[0:1], 0, v1, s[0:1]
	v_add_co_u32_e64 v74, s[0:1], s54, v168
	s_waitcnt vmcnt(14)
	v_mfma_f32_32x32x16_bf16 v[36:51], v[76:79], v[52:55], v[36:51]
	v_addc_co_u32_e64 v75, s[0:1], 0, v169, s[0:1]
	global_load_dwordx4 v[100:103], v[72:73], off
	global_load_dwordx4 v[76:79], v[72:73], off offset:1024
	global_load_dwordx4 v[104:107], v[74:75], off
	global_load_dwordx4 v[80:83], v[74:75], off offset:1024
	global_load_dwordx4 v[152:155], v[72:73], off offset:2048
	global_load_dwordx4 v[112:115], v[72:73], off offset:3072
	s_waitcnt vmcnt(19)
	v_mfma_f32_32x32x16_bf16 v[36:51], v[96:99], v[64:67], v[36:51]
	global_load_dwordx4 v[96:99], v[74:75], off offset:2048
	s_nop 0
	global_load_dwordx4 v[72:75], v[74:75], off offset:3072
	s_waitcnt vmcnt(19)
	v_mfma_f32_32x32x16_bf16 v[36:51], v[124:127], v[60:63], v[36:51]
	s_nop 11
	v_max_f32_e32 v124, v37, v37
	v_max_f32_e32 v125, v36, v36
	v_max_f32_e32 v124, v125, v124
	v_max3_f32 v124, v124, v38, v39
	v_max3_f32 v124, v124, v40, v41
	v_max3_f32 v124, v124, v42, v43
	v_max3_f32 v124, v124, v44, v45
	v_max3_f32 v124, v124, v46, v47
	v_max3_f32 v124, v124, v48, v49
	v_max3_f32 v124, v124, v50, v51
	v_mul_f32_e32 v124, 0x3e38aa3b, v124
	v_mfma_f32_32x32x16_bf16 v[4:19], v[120:123], v[132:135], v[4:19]
	ds_bpermute_b32 v125, v224, v124
	s_waitcnt lgkmcnt(0)
	v_max3_f32 v120, v3, v124, v125
	v_cmp_gt_f32_e32 vcc, v120, v3
	s_cbranch_vccz .LBB0_1059
	v_sub_f32_e32 v3, v3, v120
	v_exp_f32_e32 v122, v3
	v_mov_b32_e32 v3, v120
	v_mul_f32_e32 v164, v164, v122
	v_pk_mul_f32 v[34:35], v[34:35], v[122:123] op_sel_hi:[1,0]
	v_pk_mul_f32 v[32:33], v[32:33], v[122:123] op_sel_hi:[1,0]
	v_pk_mul_f32 v[30:31], v[30:31], v[122:123] op_sel_hi:[1,0]
	v_pk_mul_f32 v[28:29], v[28:29], v[122:123] op_sel_hi:[1,0]
	v_pk_mul_f32 v[26:27], v[26:27], v[122:123] op_sel_hi:[1,0]
	v_pk_mul_f32 v[24:25], v[24:25], v[122:123] op_sel_hi:[1,0]
	v_pk_mul_f32 v[22:23], v[22:23], v[122:123] op_sel_hi:[1,0]
	v_pk_mul_f32 v[20:21], v[20:21], v[122:123] op_sel_hi:[1,0]
	v_pk_mul_f32 v[18:19], v[18:19], v[122:123] op_sel_hi:[1,0]
	v_pk_mul_f32 v[16:17], v[16:17], v[122:123] op_sel_hi:[1,0]
	v_pk_mul_f32 v[14:15], v[14:15], v[122:123] op_sel_hi:[1,0]
	v_pk_mul_f32 v[12:13], v[12:13], v[122:123] op_sel_hi:[1,0]
	v_pk_mul_f32 v[10:11], v[10:11], v[122:123] op_sel_hi:[1,0]
	v_pk_mul_f32 v[8:9], v[8:9], v[122:123] op_sel_hi:[1,0]
	v_pk_mul_f32 v[6:7], v[6:7], v[122:123] op_sel_hi:[1,0]
	v_pk_mul_f32 v[4:5], v[4:5], v[122:123] op_sel_hi:[1,0]

.LBB0_1397:
	s_waitcnt lgkmcnt(3)
	v_lshl_add_u64 v[98:99], s[30:31], 0, v[80:81]
	v_add_co_u32_e32 v94, vcc, 0x1100000, v98
	s_nop 1
	v_addc_co_u32_e32 v95, vcc, 0, v99, vcc
	global_load_dwordx4 v[94:97], v[94:95], off
	v_lshl_add_u64 v[98:99], v[98:99], 0, s[12:13]
	s_waitcnt lgkmcnt(1)
	global_load_dwordx4 v[98:101], v[98:99], off offset:16
	s_waitcnt vmcnt(1)
	v_lshlrev_b32_e32 v93, 16, v94
	v_and_b32_e32 v94, 0xffff0000, v94
	v_fma_f32 v109, v8, v93, 0
	v_fma_f32 v110, v24, v93, 0
	v_fma_f32 v111, v40, v93, 0
	v_fma_f32 v112, v56, v93, 0
	v_fma_f32 v93, v72, v93, 0
	s_waitcnt lgkmcnt(0)
	v_lshlrev_b32_e32 v102, 16, v95
	v_fmac_f32_e32 v109, v9, v94
	v_fmac_f32_e32 v110, v25, v94
	v_fmac_f32_e32 v111, v41, v94
	v_fmac_f32_e32 v112, v57, v94
	v_fmac_f32_e32 v93, v73, v94
	v_and_b32_e32 v95, 0xffff0000, v95
	v_fmac_f32_e32 v109, v10, v102
	v_fmac_f32_e32 v110, v26, v102
	v_fmac_f32_e32 v111, v42, v102
	v_fmac_f32_e32 v112, v58, v102
	v_fmac_f32_e32 v93, v74, v102
	v_lshlrev_b32_e32 v103, 16, v96
	v_fmac_f32_e32 v109, v11, v95
	v_fmac_f32_e32 v110, v27, v95
	v_fmac_f32_e32 v111, v43, v95
	v_fmac_f32_e32 v112, v59, v95
	v_fmac_f32_e32 v93, v75, v95
	v_and_b32_e32 v96, 0xffff0000, v96
	v_fmac_f32_e32 v109, v0, v103
	v_fmac_f32_e32 v110, v16, v103
	v_fmac_f32_e32 v111, v32, v103
	v_fmac_f32_e32 v112, v48, v103
	v_fmac_f32_e32 v93, v64, v103
	v_lshlrev_b32_e32 v104, 16, v97
	v_fmac_f32_e32 v109, v1, v96
	v_fmac_f32_e32 v110, v17, v96
	v_fmac_f32_e32 v111, v33, v96
	v_fmac_f32_e32 v112, v49, v96
	v_fmac_f32_e32 v93, v65, v96
	v_and_b32_e32 v97, 0xffff0000, v97
	v_fmac_f32_e32 v109, v2, v104
	v_fmac_f32_e32 v110, v18, v104
	v_fmac_f32_e32 v111, v34, v104
	v_fmac_f32_e32 v112, v50, v104
	v_fmac_f32_e32 v93, v66, v104
	s_waitcnt vmcnt(0)
	v_lshlrev_b32_e32 v105, 16, v98
	v_fmac_f32_e32 v109, v3, v97
	v_fmac_f32_e32 v110, v19, v97
	v_fmac_f32_e32 v111, v35, v97
	v_fmac_f32_e32 v112, v51, v97
	v_fmac_f32_e32 v93, v67, v97
	v_and_b32_e32 v98, 0xffff0000, v98
	v_fmac_f32_e32 v109, v4, v105
	v_fmac_f32_e32 v110, v20, v105
	v_fmac_f32_e32 v111, v36, v105
	v_fmac_f32_e32 v112, v52, v105
	v_fmac_f32_e32 v93, v68, v105
	v_lshlrev_b32_e32 v106, 16, v99
	v_fmac_f32_e32 v109, v5, v98
	v_fmac_f32_e32 v110, v21, v98
	v_fmac_f32_e32 v111, v37, v98
	v_fmac_f32_e32 v112, v53, v98
	v_fmac_f32_e32 v93, v69, v98
	v_and_b32_e32 v99, 0xffff0000, v99
	v_fmac_f32_e32 v109, v6, v106
	v_fmac_f32_e32 v110, v22, v106
	v_fmac_f32_e32 v111, v38, v106
	v_fmac_f32_e32 v112, v54, v106
	v_fmac_f32_e32 v93, v70, v106
	v_lshlrev_b32_e32 v107, 16, v100
	v_fmac_f32_e32 v109, v7, v99
	v_fmac_f32_e32 v110, v23, v99
	v_fmac_f32_e32 v111, v39, v99
	v_fmac_f32_e32 v112, v55, v99
	v_fmac_f32_e32 v93, v71, v99
	v_and_b32_e32 v100, 0xffff0000, v100
	v_fmac_f32_e32 v109, v12, v107
	v_fmac_f32_e32 v110, v28, v107
	v_fmac_f32_e32 v111, v44, v107
	v_fmac_f32_e32 v112, v60, v107
	v_fmac_f32_e32 v93, v76, v107
	v_lshlrev_b32_e32 v108, 16, v101
	v_fmac_f32_e32 v109, v13, v100
	v_fmac_f32_e32 v110, v29, v100
	v_fmac_f32_e32 v111, v45, v100
	v_fmac_f32_e32 v112, v61, v100
	v_fmac_f32_e32 v93, v77, v100
	v_and_b32_e32 v101, 0xffff0000, v101
	v_fmac_f32_e32 v109, v14, v108
	v_fmac_f32_e32 v110, v30, v108
	v_fmac_f32_e32 v111, v46, v108
	v_fmac_f32_e32 v112, v62, v108
	v_fmac_f32_e32 v93, v78, v108
	v_fmac_f32_e32 v109, v15, v101
	v_fmac_f32_e32 v110, v31, v101
	v_fmac_f32_e32 v111, v47, v101
	v_fmac_f32_e32 v112, v63, v101
	v_fmac_f32_e32 v93, v79, v101
	ds_bpermute_b32 v94, v82, v109
	ds_bpermute_b32 v95, v82, v110
	ds_bpermute_b32 v96, v82, v111
	ds_bpermute_b32 v97, v82, v112
	ds_bpermute_b32 v98, v82, v93
	s_waitcnt lgkmcnt(4)
	v_add_f32_e32 v94, v109, v94
	s_waitcnt lgkmcnt(3)
	v_add_f32_e32 v95, v110, v95
	s_waitcnt lgkmcnt(2)
	v_add_f32_e32 v96, v111, v96
	s_waitcnt lgkmcnt(1)
	v_add_f32_e32 v97, v112, v97
	s_waitcnt lgkmcnt(0)
	v_add_f32_e32 v93, v93, v98
	ds_bpermute_b32 v98, v83, v94
	ds_bpermute_b32 v99, v83, v95
	ds_bpermute_b32 v100, v83, v96
	ds_bpermute_b32 v101, v83, v97
	ds_bpermute_b32 v102, v83, v93
	s_waitcnt lgkmcnt(4)
	v_add_f32_e32 v94, v94, v98
	s_waitcnt lgkmcnt(3)
	v_add_f32_e32 v95, v95, v99
	s_waitcnt lgkmcnt(2)
	v_add_f32_e32 v96, v96, v100
	s_waitcnt lgkmcnt(1)
	v_add_f32_e32 v97, v97, v101
	s_waitcnt lgkmcnt(0)
	v_add_f32_e32 v93, v93, v102
	ds_bpermute_b32 v98, v84, v94
	ds_bpermute_b32 v99, v84, v95
	ds_bpermute_b32 v100, v84, v96
	ds_bpermute_b32 v101, v84, v97
	ds_bpermute_b32 v102, v84, v93
	s_waitcnt lgkmcnt(4)
	v_add_f32_e32 v94, v94, v98
	s_waitcnt lgkmcnt(3)
	v_add_f32_e32 v95, v95, v99
	s_waitcnt lgkmcnt(2)
	v_add_f32_e32 v96, v96, v100
	s_waitcnt lgkmcnt(1)
	v_add_f32_e32 v97, v97, v101
	s_waitcnt lgkmcnt(0)
	v_add_f32_e32 v93, v93, v102
	ds_bpermute_b32 v98, v85, v94
	ds_bpermute_b32 v99, v85, v95
	ds_bpermute_b32 v100, v85, v96
	ds_bpermute_b32 v101, v85, v97
	ds_bpermute_b32 v102, v85, v93
	s_waitcnt lgkmcnt(4)
	v_add_f32_e32 v94, v94, v98
	s_waitcnt lgkmcnt(3)
	v_add_f32_e32 v95, v95, v99
	s_waitcnt lgkmcnt(2)
	v_add_f32_e32 v96, v96, v100
	s_waitcnt lgkmcnt(1)
	v_add_f32_e32 v97, v97, v101
	s_waitcnt lgkmcnt(0)
	v_add_f32_e32 v98, v93, v102
	ds_bpermute_b32 v93, v86, v94
	ds_bpermute_b32 v99, v86, v95
	ds_bpermute_b32 v100, v86, v96
	ds_bpermute_b32 v101, v86, v97
	ds_bpermute_b32 v102, v86, v98
	s_waitcnt lgkmcnt(4)
	v_add_f32_e32 v93, v94, v93
	s_waitcnt lgkmcnt(3)
	v_add_f32_e32 v94, v95, v99
	s_waitcnt lgkmcnt(2)
	v_add_f32_e32 v95, v96, v100
	s_waitcnt lgkmcnt(1)
	v_add_f32_e32 v97, v97, v101
	s_waitcnt lgkmcnt(0)
	v_add_f32_e32 v99, v98, v102
	ds_bpermute_b32 v96, v87, v93
	ds_bpermute_b32 v98, v87, v94
	ds_bpermute_b32 v100, v87, v95
	ds_bpermute_b32 v101, v87, v97
	ds_bpermute_b32 v102, v87, v99
	s_and_saveexec_b64 s[10:11], s[2:3]
	s_cbranch_execz .LBB0_1396
	s_add_u32 s14, s30, s0
	s_waitcnt lgkmcnt(4)
	v_add_f32_e32 v93, v93, v96
	s_addc_u32 s15, s31, s1
	s_waitcnt lgkmcnt(0)
	v_add_f32_e32 v99, v99, v102
	v_add_f32_e32 v97, v97, v101
	v_add_f32_e32 v95, v95, v100
	v_add_f32_e32 v94, v94, v98
	global_store_dword v88, v93, s[14:15] sc0 sc1
	global_store_dword v89, v94, s[14:15] offset:2048 sc0 sc1
	global_store_dword v90, v95, s[14:15] sc0 sc1
	global_store_dword v91, v97, s[14:15] offset:2048 sc0 sc1
	global_store_dword v92, v99, s[14:15] sc0 sc1
	s_branch .LBB0_1396

.Lp5_tail:
	s_cmp_gt_i32 s69, 6
	s_cselect_b64 s[0:1], -1, 0
	s_and_b64 s[2:3], s[4:5], s[0:1]
	s_andn2_b64 vcc, exec, s[2:3]
	s_cbranch_vccnz .LBB0_1453
	s_cmp_eq_u32 s98, 2
	s_cbranch_scc0 .Lsb_orig
	s_waitcnt vmcnt(0) lgkmcnt(0)
	s_barrier
	s_mov_b32 s98, 3
	v_cmp_gt_u32_e32 vcc, 64, v199
	s_cbranch_vccz .Lsb_done
	s_lshl_b32 s6, s33, 8
	s_add_u32 s6, s92, s6
	s_addc_u32 s7, s93, 0
	v_mov_b32_e32 v0, 0x1400
	v_mov_b32_e32 v1, 1
	s_lshl_b32 s10, s33, 7
	s_add_u32 s10, s10, 0x3600
	v_lshl_add_u32 v4, v199, 2, s10
	v_cmp_eq_u32_e32 vcc, 0, v199
	s_and_saveexec_b64 s[12:13], vcc
	global_atomic_add v2, v0, v1, s[6:7] sc0
	s_mov_b64 exec, s[12:13]
	s_waitcnt vmcnt(0)
	v_readfirstlane_b32 s11, v2
	s_nop 3
	s_lshr_b32 s99, s11, 5
	s_and_b32 s11, s11, 31
	s_cmp_eq_u32 s11, 31
	s_cbranch_scc0 .Lsb_waitA
	v_mov_b32_e32 v0, 0xfc03000
	s_and_saveexec_b64 s[12:13], vcc
	global_atomic_add v2, v0, v1, s[30:31] offset:1024 sc0
	s_mov_b64 exec, s[12:13]
	s_waitcnt vmcnt(0)
	v_readfirstlane_b32 s11, v2
	s_nop 3
	s_and_b32 s11, s11, 7
	s_cmp_eq_u32 s11, 7
	s_cbranch_scc0 .Lsb_waitA
	v_mov_b32_e32 v0, 0xfc03500
	s_and_saveexec_b64 s[12:13], vcc
	global_atomic_add v0, v1, s[30:31]
	s_mov_b64 exec, s[12:13]
